# V45 + hand-written GDN prep conv+silu stage for prompt units (8 tokens side by side, raw rows read up front)
# speedup vs baseline: 1.0205x; 1.0170x over previous
.LBB0_575:
	v_ashrrev_i32_e32 v29, 6, v96
	v_bfe_u32 v36, v96, 5, 1
	v_lshl_or_b32 v40, v29, 1, v36
	v_lshlrev_b32_e32 v49, 1, v42
	v_lshlrev_b32_e32 v36, 10, v40
	v_add_u32_e32 v38, v49, v36
	s_ashr_i32 s68, s94, 3
	v_add_u32_e32 v36, 0x6c00, v38
	s_cmpk_gt_i32 s68, 0x1ff
	s_waitcnt lgkmcnt(0)
	s_barrier
	s_cbranch_scc0 .Lcv_fast
	ds_read2_b32 v[94:95], v36 offset1:32
	ds_read_b32 v60, v38 offset:27904
	s_cselect_b64 s[4:5], -1, 0
	s_and_b64 s[0:1], s[4:5], exec
	s_cselect_b32 s95, 16, 64
	v_lshlrev_b32_e32 v52, 3, v40
	v_cmp_gt_i32_e32 vcc, s95, v52
	v_mov_b32_e32 v42, 0
	v_mov_b32_e32 v93, 0
	v_mov_b32_e32 v56, 0
	s_and_saveexec_b64 s[0:1], vcc
	s_cbranch_execz .LBB0_577
	ds_read_b32 v36, v38 offset:28032
	s_waitcnt lgkmcnt(0)
	v_lshlrev_b32_e32 v93, 16, v36
	v_and_b32_e32 v56, 0xffff0000, v36

.LBB0_671:
	s_or_b64 exec, exec, s[0:1]
	v_mul_f32_e32 v41, v41, v42
	v_fmac_f32_e32 v41, v37, v40
	v_fmac_f32_e32 v41, v39, v38
	v_fmac_f32_e32 v41, v43, v52
	v_mul_f32_e32 v37, 0xbfb8aa3b, v41
	v_exp_f32_e32 v37, v37
	v_and_b32_e32 v167, 63, v96
	v_cmp_gt_i32_e64 s[8:9], 64, v96
	v_add_f32_e32 v37, 1.0, v37
	v_rcp_f32_e32 v37, v37
	s_nop 0
	v_mul_f32_e32 v37, v41, v37
	v_cndmask_b32_e64 v37, 0, v37, s[16:17]
	v_cvt_pk_bf16_f32 v37, v48, v37
	ds_write_b32 v36, v37 offset:19296
	s_branch .Lcv_join
.Lcv_fast:
	v_and_b32_e32 v36, 31, v96
	v_lshrrev_b32_e32 v38, 5, v96
	s_movk_i32 s0, 0x480
	v_lshlrev_b32_e32 v36, 2, v36
	v_mad_u32_u24 v89, v38, s0, v36
	v_lshl_add_u32 v36, v38, 10, v36
	v_mov_b32_e32 v38, v89
	ds_read_b32 v40, v36 offset:27648
	ds_read_b32 v42, v36 offset:27776
	ds_read_b32 v48, v36 offset:27904
	ds_read_b32 v49, v36 offset:28032
	ds_read_b32 v50, v36 offset:28160
	ds_read_b32 v51, v36 offset:28288
	ds_read_b32 v52, v36 offset:28416
	ds_read_b32 v54, v36 offset:28544
	ds_read_b32 v55, v36 offset:28672
	ds_read_b32 v56, v36 offset:28800
	ds_read_b32 v58, v36 offset:28928
	s_waitcnt lgkmcnt(0)
	v_lshlrev_b32_e32 v60, 16, v40
	v_lshlrev_b32_e32 v63, 16, v42
	v_lshlrev_b32_e32 v68, 16, v48
	v_lshlrev_b32_e32 v69, 16, v49
	v_lshlrev_b32_e32 v70, 16, v50
	v_lshlrev_b32_e32 v72, 16, v51
	v_lshlrev_b32_e32 v74, 16, v52
	v_lshlrev_b32_e32 v76, 16, v54
	v_lshlrev_b32_e32 v86, 16, v55
	v_lshlrev_b32_e32 v87, 16, v56
	v_lshlrev_b32_e32 v88, 16, v58
	v_and_b32_e32 v40, 0xffff0000, v40
	v_and_b32_e32 v42, 0xffff0000, v42
	v_and_b32_e32 v48, 0xffff0000, v48
	v_and_b32_e32 v49, 0xffff0000, v49
	v_and_b32_e32 v50, 0xffff0000, v50
	v_and_b32_e32 v51, 0xffff0000, v51
	v_and_b32_e32 v52, 0xffff0000, v52
	v_and_b32_e32 v54, 0xffff0000, v54
	v_and_b32_e32 v55, 0xffff0000, v55
	v_and_b32_e32 v56, 0xffff0000, v56
	v_and_b32_e32 v58, 0xffff0000, v58
	v_mul_f32_e32 v89, v85, v63
	v_mul_f32_e32 v90, v85, v68
	v_mul_f32_e32 v91, v85, v69
	v_mul_f32_e32 v92, v85, v70
	v_mul_f32_e32 v93, v85, v72
	v_mul_f32_e32 v94, v85, v74
	v_mul_f32_e32 v95, v85, v76
	v_mul_f32_e32 v245, v85, v86
	v_mul_f32_e32 v246, v75, v42
	v_mul_f32_e32 v247, v75, v48
	v_mul_f32_e32 v248, v75, v49
	v_mul_f32_e32 v249, v75, v50
	v_mul_f32_e32 v250, v75, v51
	v_mul_f32_e32 v251, v75, v52
	v_mul_f32_e32 v252, v75, v54
	v_mul_f32_e32 v253, v75, v55
	v_fmac_f32_e32 v89, v84, v60
	v_fmac_f32_e32 v90, v84, v63
	v_fmac_f32_e32 v91, v84, v68
	v_fmac_f32_e32 v92, v84, v69
	v_fmac_f32_e32 v93, v84, v70
	v_fmac_f32_e32 v94, v84, v72
	v_fmac_f32_e32 v95, v84, v74
	v_fmac_f32_e32 v245, v84, v76
	v_fmac_f32_e32 v246, v71, v40
	v_fmac_f32_e32 v247, v71, v42
	v_fmac_f32_e32 v248, v71, v48
	v_fmac_f32_e32 v249, v71, v49
	v_fmac_f32_e32 v250, v71, v50
	v_fmac_f32_e32 v251, v71, v51
	v_fmac_f32_e32 v252, v71, v52
	v_fmac_f32_e32 v253, v71, v54
	v_fmac_f32_e32 v89, v82, v68
	v_fmac_f32_e32 v90, v82, v69
	v_fmac_f32_e32 v91, v82, v70
	v_fmac_f32_e32 v92, v82, v72
	v_fmac_f32_e32 v93, v82, v74
	v_fmac_f32_e32 v94, v82, v76
	v_fmac_f32_e32 v95, v82, v86
	v_fmac_f32_e32 v245, v82, v87
	v_fmac_f32_e32 v246, v73, v48
	v_fmac_f32_e32 v247, v73, v49
	v_fmac_f32_e32 v248, v73, v50
	v_fmac_f32_e32 v249, v73, v51
	v_fmac_f32_e32 v250, v73, v52
	v_fmac_f32_e32 v251, v73, v54
	v_fmac_f32_e32 v252, v73, v55
	v_fmac_f32_e32 v253, v73, v56
	v_fmac_f32_e32 v89, v83, v69
	v_fmac_f32_e32 v90, v83, v70
	v_fmac_f32_e32 v91, v83, v72
	v_fmac_f32_e32 v92, v83, v74
	v_fmac_f32_e32 v93, v83, v76
	v_fmac_f32_e32 v94, v83, v86
	v_fmac_f32_e32 v95, v83, v87
	v_fmac_f32_e32 v245, v83, v88
	v_fmac_f32_e32 v246, v77, v49
	v_fmac_f32_e32 v247, v77, v50
	v_fmac_f32_e32 v248, v77, v51
	v_fmac_f32_e32 v249, v77, v52
	v_fmac_f32_e32 v250, v77, v54
	v_fmac_f32_e32 v251, v77, v55
	v_fmac_f32_e32 v252, v77, v56
	v_fmac_f32_e32 v253, v77, v58
	ds_read_b32 v40, v36 offset:36224
	ds_read_b32 v42, v36 offset:36352
	ds_read_b32 v48, v36 offset:36480
	ds_read_b32 v49, v36 offset:36608
	ds_read_b32 v50, v36 offset:36736
	ds_read_b32 v51, v36 offset:36864
	ds_read_b32 v52, v36 offset:36992
	ds_read_b32 v54, v36 offset:37120
	ds_read_b32 v55, v36 offset:37248
	ds_read_b32 v56, v36 offset:37376
	ds_read_b32 v58, v36 offset:37504
	v_mul_f32_e32 v60, 0xbfb8aa3b, v89
	v_mul_f32_e32 v63, 0xbfb8aa3b, v90
	v_mul_f32_e32 v68, 0xbfb8aa3b, v91
	v_mul_f32_e32 v69, 0xbfb8aa3b, v92
	v_mul_f32_e32 v70, 0xbfb8aa3b, v93
	v_mul_f32_e32 v72, 0xbfb8aa3b, v94
	v_mul_f32_e32 v74, 0xbfb8aa3b, v95
	v_mul_f32_e32 v76, 0xbfb8aa3b, v245
	v_exp_f32_e32 v60, v60
	v_exp_f32_e32 v63, v63
	v_exp_f32_e32 v68, v68
	v_exp_f32_e32 v69, v69
	v_exp_f32_e32 v70, v70
	v_exp_f32_e32 v72, v72
	v_exp_f32_e32 v74, v74
	v_exp_f32_e32 v76, v76
	v_add_f32_e32 v60, 1.0, v60
	v_add_f32_e32 v63, 1.0, v63
	v_add_f32_e32 v68, 1.0, v68
	v_add_f32_e32 v69, 1.0, v69
	v_add_f32_e32 v70, 1.0, v70
	v_add_f32_e32 v72, 1.0, v72
	v_add_f32_e32 v74, 1.0, v74
	v_add_f32_e32 v76, 1.0, v76
	v_rcp_f32_e32 v60, v60
	v_rcp_f32_e32 v63, v63
	v_rcp_f32_e32 v68, v68
	v_rcp_f32_e32 v69, v69
	v_rcp_f32_e32 v70, v70
	v_rcp_f32_e32 v72, v72
	v_rcp_f32_e32 v74, v74
	v_rcp_f32_e32 v76, v76
	v_mul_f32_e32 v89, v89, v60
	v_mul_f32_e32 v90, v90, v63
	v_mul_f32_e32 v91, v91, v68
	v_mul_f32_e32 v92, v92, v69
	v_mul_f32_e32 v93, v93, v70
	v_mul_f32_e32 v94, v94, v72
	v_mul_f32_e32 v95, v95, v74
	v_mul_f32_e32 v245, v245, v76
	v_mul_f32_e32 v60, 0xbfb8aa3b, v246
	v_mul_f32_e32 v63, 0xbfb8aa3b, v247
	v_mul_f32_e32 v68, 0xbfb8aa3b, v248
	v_mul_f32_e32 v69, 0xbfb8aa3b, v249
	v_mul_f32_e32 v70, 0xbfb8aa3b, v250
	v_mul_f32_e32 v72, 0xbfb8aa3b, v251
	v_mul_f32_e32 v74, 0xbfb8aa3b, v252
	v_mul_f32_e32 v76, 0xbfb8aa3b, v253
	v_exp_f32_e32 v60, v60
	v_exp_f32_e32 v63, v63
	v_exp_f32_e32 v68, v68
	v_exp_f32_e32 v69, v69
	v_exp_f32_e32 v70, v70
	v_exp_f32_e32 v72, v72
	v_exp_f32_e32 v74, v74
	v_exp_f32_e32 v76, v76
	v_add_f32_e32 v60, 1.0, v60
	v_add_f32_e32 v63, 1.0, v63
	v_add_f32_e32 v68, 1.0, v68
	v_add_f32_e32 v69, 1.0, v69
	v_add_f32_e32 v70, 1.0, v70
	v_add_f32_e32 v72, 1.0, v72
	v_add_f32_e32 v74, 1.0, v74
	v_add_f32_e32 v76, 1.0, v76
	v_rcp_f32_e32 v60, v60
	v_rcp_f32_e32 v63, v63
	v_rcp_f32_e32 v68, v68
	v_rcp_f32_e32 v69, v69
	v_rcp_f32_e32 v70, v70
	v_rcp_f32_e32 v72, v72
	v_rcp_f32_e32 v74, v74
	v_rcp_f32_e32 v76, v76
	v_mul_f32_e32 v246, v246, v60
	v_mul_f32_e32 v247, v247, v63
	v_mul_f32_e32 v248, v248, v68
	v_mul_f32_e32 v249, v249, v69
	v_mul_f32_e32 v250, v250, v70
	v_mul_f32_e32 v251, v251, v72
	v_mul_f32_e32 v252, v252, v74
	v_mul_f32_e32 v253, v253, v76
	v_cvt_pk_bf16_f32 v89, v89, v246
	v_cvt_pk_bf16_f32 v90, v90, v247
	v_cvt_pk_bf16_f32 v91, v91, v248
	v_cvt_pk_bf16_f32 v92, v92, v249
	v_cvt_pk_bf16_f32 v93, v93, v250
	v_cvt_pk_bf16_f32 v94, v94, v251
	v_cvt_pk_bf16_f32 v95, v95, v252
	v_cvt_pk_bf16_f32 v245, v245, v253
	ds_write_b32 v38, v89
	ds_write_b32 v38, v90 offset:144
	ds_write_b32 v38, v91 offset:288
	ds_write_b32 v38, v92 offset:432
	ds_write_b32 v38, v93 offset:576
	ds_write_b32 v38, v94 offset:720
	ds_write_b32 v38, v95 offset:864
	ds_write_b32 v38, v245 offset:1008
	s_waitcnt lgkmcnt(8)
	v_lshlrev_b32_e32 v60, 16, v40
	v_lshlrev_b32_e32 v63, 16, v42
	v_lshlrev_b32_e32 v68, 16, v48
	v_lshlrev_b32_e32 v69, 16, v49
	v_lshlrev_b32_e32 v70, 16, v50
	v_lshlrev_b32_e32 v72, 16, v51
	v_lshlrev_b32_e32 v74, 16, v52
	v_lshlrev_b32_e32 v76, 16, v54
	v_lshlrev_b32_e32 v86, 16, v55
	v_lshlrev_b32_e32 v87, 16, v56
	v_lshlrev_b32_e32 v88, 16, v58
	v_and_b32_e32 v40, 0xffff0000, v40
	v_and_b32_e32 v42, 0xffff0000, v42
	v_and_b32_e32 v48, 0xffff0000, v48
	v_and_b32_e32 v49, 0xffff0000, v49
	v_and_b32_e32 v50, 0xffff0000, v50
	v_and_b32_e32 v51, 0xffff0000, v51
	v_and_b32_e32 v52, 0xffff0000, v52
	v_and_b32_e32 v54, 0xffff0000, v54
	v_and_b32_e32 v55, 0xffff0000, v55
	v_and_b32_e32 v56, 0xffff0000, v56
	v_and_b32_e32 v58, 0xffff0000, v58
	v_mul_f32_e32 v89, v67, v63
	v_mul_f32_e32 v90, v67, v68
	v_mul_f32_e32 v91, v67, v69
	v_mul_f32_e32 v92, v67, v70
	v_mul_f32_e32 v93, v67, v72
	v_mul_f32_e32 v94, v67, v74
	v_mul_f32_e32 v95, v67, v76
	v_mul_f32_e32 v245, v67, v86
	v_mul_f32_e32 v246, v59, v42
	v_mul_f32_e32 v247, v59, v48
	v_mul_f32_e32 v248, v59, v49
	v_mul_f32_e32 v249, v59, v50
	v_mul_f32_e32 v250, v59, v51
	v_mul_f32_e32 v251, v59, v52
	v_mul_f32_e32 v252, v59, v54
	v_mul_f32_e32 v253, v59, v55
	v_fmac_f32_e32 v89, v66, v60
	v_fmac_f32_e32 v90, v66, v63
	v_fmac_f32_e32 v91, v66, v68
	v_fmac_f32_e32 v92, v66, v69
	v_fmac_f32_e32 v93, v66, v70
	v_fmac_f32_e32 v94, v66, v72
	v_fmac_f32_e32 v95, v66, v74
	v_fmac_f32_e32 v245, v66, v76
	v_fmac_f32_e32 v246, v53, v40
	v_fmac_f32_e32 v247, v53, v42
	v_fmac_f32_e32 v248, v53, v48
	v_fmac_f32_e32 v249, v53, v49
	v_fmac_f32_e32 v250, v53, v50
	v_fmac_f32_e32 v251, v53, v51
	v_fmac_f32_e32 v252, v53, v52
	v_fmac_f32_e32 v253, v53, v54
	v_fmac_f32_e32 v89, v64, v68
	v_fmac_f32_e32 v90, v64, v69
	v_fmac_f32_e32 v91, v64, v70
	v_fmac_f32_e32 v92, v64, v72
	v_fmac_f32_e32 v93, v64, v74
	v_fmac_f32_e32 v94, v64, v76
	v_fmac_f32_e32 v95, v64, v86
	v_fmac_f32_e32 v245, v64, v87
	v_fmac_f32_e32 v246, v57, v48
	v_fmac_f32_e32 v247, v57, v49
	v_fmac_f32_e32 v248, v57, v50
	v_fmac_f32_e32 v249, v57, v51
	v_fmac_f32_e32 v250, v57, v52
	v_fmac_f32_e32 v251, v57, v54
	v_fmac_f32_e32 v252, v57, v55
	v_fmac_f32_e32 v253, v57, v56
	v_fmac_f32_e32 v89, v65, v69
	v_fmac_f32_e32 v90, v65, v70
	v_fmac_f32_e32 v91, v65, v72
	v_fmac_f32_e32 v92, v65, v74
	v_fmac_f32_e32 v93, v65, v76
	v_fmac_f32_e32 v94, v65, v86
	v_fmac_f32_e32 v95, v65, v87
	v_fmac_f32_e32 v245, v65, v88
	v_fmac_f32_e32 v246, v61, v49
	v_fmac_f32_e32 v247, v61, v50
	v_fmac_f32_e32 v248, v61, v51
	v_fmac_f32_e32 v249, v61, v52
	v_fmac_f32_e32 v250, v61, v54
	v_fmac_f32_e32 v251, v61, v55
	v_fmac_f32_e32 v252, v61, v56
	v_fmac_f32_e32 v253, v61, v58
	ds_read_b32 v40, v36 offset:44800
	ds_read_b32 v42, v36 offset:44928
	ds_read_b32 v48, v36 offset:45056
	ds_read_b32 v49, v36 offset:45184
	ds_read_b32 v50, v36 offset:45312
	ds_read_b32 v51, v36 offset:45440
	ds_read_b32 v52, v36 offset:45568
	ds_read_b32 v54, v36 offset:45696
	ds_read_b32 v55, v36 offset:45824
	ds_read_b32 v56, v36 offset:45952
	ds_read_b32 v58, v36 offset:46080
	v_mul_f32_e32 v60, 0xbfb8aa3b, v89
	v_mul_f32_e32 v63, 0xbfb8aa3b, v90
	v_mul_f32_e32 v68, 0xbfb8aa3b, v91
	v_mul_f32_e32 v69, 0xbfb8aa3b, v92
	v_mul_f32_e32 v70, 0xbfb8aa3b, v93
	v_mul_f32_e32 v72, 0xbfb8aa3b, v94
	v_mul_f32_e32 v74, 0xbfb8aa3b, v95
	v_mul_f32_e32 v76, 0xbfb8aa3b, v245
	v_exp_f32_e32 v60, v60
	v_exp_f32_e32 v63, v63
	v_exp_f32_e32 v68, v68
	v_exp_f32_e32 v69, v69
	v_exp_f32_e32 v70, v70
	v_exp_f32_e32 v72, v72
	v_exp_f32_e32 v74, v74
	v_exp_f32_e32 v76, v76
	v_add_f32_e32 v60, 1.0, v60
	v_add_f32_e32 v63, 1.0, v63
	v_add_f32_e32 v68, 1.0, v68
	v_add_f32_e32 v69, 1.0, v69
	v_add_f32_e32 v70, 1.0, v70
	v_add_f32_e32 v72, 1.0, v72
	v_add_f32_e32 v74, 1.0, v74
	v_add_f32_e32 v76, 1.0, v76
	v_rcp_f32_e32 v60, v60
	v_rcp_f32_e32 v63, v63
	v_rcp_f32_e32 v68, v68
	v_rcp_f32_e32 v69, v69
	v_rcp_f32_e32 v70, v70
	v_rcp_f32_e32 v72, v72
	v_rcp_f32_e32 v74, v74
	v_rcp_f32_e32 v76, v76
	v_mul_f32_e32 v89, v89, v60
	v_mul_f32_e32 v90, v90, v63
	v_mul_f32_e32 v91, v91, v68
	v_mul_f32_e32 v92, v92, v69
	v_mul_f32_e32 v93, v93, v70
	v_mul_f32_e32 v94, v94, v72
	v_mul_f32_e32 v95, v95, v74
	v_mul_f32_e32 v245, v245, v76
	v_mul_f32_e32 v60, 0xbfb8aa3b, v246
	v_mul_f32_e32 v63, 0xbfb8aa3b, v247
	v_mul_f32_e32 v68, 0xbfb8aa3b, v248
	v_mul_f32_e32 v69, 0xbfb8aa3b, v249
	v_mul_f32_e32 v70, 0xbfb8aa3b, v250
	v_mul_f32_e32 v72, 0xbfb8aa3b, v251
	v_mul_f32_e32 v74, 0xbfb8aa3b, v252
	v_mul_f32_e32 v76, 0xbfb8aa3b, v253
	v_exp_f32_e32 v60, v60
	v_exp_f32_e32 v63, v63
	v_exp_f32_e32 v68, v68
	v_exp_f32_e32 v69, v69
	v_exp_f32_e32 v70, v70
	v_exp_f32_e32 v72, v72
	v_exp_f32_e32 v74, v74
	v_exp_f32_e32 v76, v76
	v_add_f32_e32 v60, 1.0, v60
	v_add_f32_e32 v63, 1.0, v63
	v_add_f32_e32 v68, 1.0, v68
	v_add_f32_e32 v69, 1.0, v69
	v_add_f32_e32 v70, 1.0, v70
	v_add_f32_e32 v72, 1.0, v72
	v_add_f32_e32 v74, 1.0, v74
	v_add_f32_e32 v76, 1.0, v76
	v_rcp_f32_e32 v60, v60
	v_rcp_f32_e32 v63, v63
	v_rcp_f32_e32 v68, v68
	v_rcp_f32_e32 v69, v69
	v_rcp_f32_e32 v70, v70
	v_rcp_f32_e32 v72, v72
	v_rcp_f32_e32 v74, v74
	v_rcp_f32_e32 v76, v76
	v_mul_f32_e32 v246, v246, v60
	v_mul_f32_e32 v247, v247, v63
	v_mul_f32_e32 v248, v248, v68
	v_mul_f32_e32 v249, v249, v69
	v_mul_f32_e32 v250, v250, v70
	v_mul_f32_e32 v251, v251, v72
	v_mul_f32_e32 v252, v252, v74
	v_mul_f32_e32 v253, v253, v76
	v_cvt_pk_bf16_f32 v89, v89, v246
	v_cvt_pk_bf16_f32 v90, v90, v247
	v_cvt_pk_bf16_f32 v91, v91, v248
	v_cvt_pk_bf16_f32 v92, v92, v249
	v_cvt_pk_bf16_f32 v93, v93, v250
	v_cvt_pk_bf16_f32 v94, v94, v251
	v_cvt_pk_bf16_f32 v95, v95, v252
	v_cvt_pk_bf16_f32 v245, v245, v253
	ds_write_b32 v38, v89 offset:9216
	ds_write_b32 v38, v90 offset:9360
	ds_write_b32 v38, v91 offset:9504
	ds_write_b32 v38, v92 offset:9648
	ds_write_b32 v38, v93 offset:9792
	ds_write_b32 v38, v94 offset:9936
	ds_write_b32 v38, v95 offset:10080
	ds_write_b32 v38, v245 offset:10224
	s_waitcnt lgkmcnt(8)
	v_lshlrev_b32_e32 v60, 16, v40
	v_lshlrev_b32_e32 v63, 16, v42
	v_lshlrev_b32_e32 v68, 16, v48
	v_lshlrev_b32_e32 v69, 16, v49
	v_lshlrev_b32_e32 v70, 16, v50
	v_lshlrev_b32_e32 v72, 16, v51
	v_lshlrev_b32_e32 v74, 16, v52
	v_lshlrev_b32_e32 v76, 16, v54
	v_lshlrev_b32_e32 v86, 16, v55
	v_lshlrev_b32_e32 v87, 16, v56
	v_lshlrev_b32_e32 v88, 16, v58
	v_and_b32_e32 v40, 0xffff0000, v40
	v_and_b32_e32 v42, 0xffff0000, v42
	v_and_b32_e32 v48, 0xffff0000, v48
	v_and_b32_e32 v49, 0xffff0000, v49
	v_and_b32_e32 v50, 0xffff0000, v50
	v_and_b32_e32 v51, 0xffff0000, v51
	v_and_b32_e32 v52, 0xffff0000, v52
	v_and_b32_e32 v54, 0xffff0000, v54
	v_and_b32_e32 v55, 0xffff0000, v55
	v_and_b32_e32 v56, 0xffff0000, v56
	v_and_b32_e32 v58, 0xffff0000, v58
	v_mul_f32_e32 v89, v47, v63
	v_mul_f32_e32 v90, v47, v68
	v_mul_f32_e32 v91, v47, v69
	v_mul_f32_e32 v92, v47, v70
	v_mul_f32_e32 v93, v47, v72
	v_mul_f32_e32 v94, v47, v74
	v_mul_f32_e32 v95, v47, v76
	v_mul_f32_e32 v245, v47, v86
	v_mul_f32_e32 v246, v41, v42
	v_mul_f32_e32 v247, v41, v48
	v_mul_f32_e32 v248, v41, v49
	v_mul_f32_e32 v249, v41, v50
	v_mul_f32_e32 v250, v41, v51
	v_mul_f32_e32 v251, v41, v52
	v_mul_f32_e32 v252, v41, v54
	v_mul_f32_e32 v253, v41, v55
	v_fmac_f32_e32 v89, v46, v60
	v_fmac_f32_e32 v90, v46, v63
	v_fmac_f32_e32 v91, v46, v68
	v_fmac_f32_e32 v92, v46, v69
	v_fmac_f32_e32 v93, v46, v70
	v_fmac_f32_e32 v94, v46, v72
	v_fmac_f32_e32 v95, v46, v74
	v_fmac_f32_e32 v245, v46, v76
	v_fmac_f32_e32 v246, v37, v40
	v_fmac_f32_e32 v247, v37, v42
	v_fmac_f32_e32 v248, v37, v48
	v_fmac_f32_e32 v249, v37, v49
	v_fmac_f32_e32 v250, v37, v50
	v_fmac_f32_e32 v251, v37, v51
	v_fmac_f32_e32 v252, v37, v52
	v_fmac_f32_e32 v253, v37, v54
	v_fmac_f32_e32 v89, v44, v68
	v_fmac_f32_e32 v90, v44, v69
	v_fmac_f32_e32 v91, v44, v70
	v_fmac_f32_e32 v92, v44, v72
	v_fmac_f32_e32 v93, v44, v74
	v_fmac_f32_e32 v94, v44, v76
	v_fmac_f32_e32 v95, v44, v86
	v_fmac_f32_e32 v245, v44, v87
	v_fmac_f32_e32 v246, v39, v48
	v_fmac_f32_e32 v247, v39, v49
	v_fmac_f32_e32 v248, v39, v50
	v_fmac_f32_e32 v249, v39, v51
	v_fmac_f32_e32 v250, v39, v52
	v_fmac_f32_e32 v251, v39, v54
	v_fmac_f32_e32 v252, v39, v55
	v_fmac_f32_e32 v253, v39, v56
	v_fmac_f32_e32 v89, v45, v69
	v_fmac_f32_e32 v90, v45, v70
	v_fmac_f32_e32 v91, v45, v72
	v_fmac_f32_e32 v92, v45, v74
	v_fmac_f32_e32 v93, v45, v76
	v_fmac_f32_e32 v94, v45, v86
	v_fmac_f32_e32 v95, v45, v87
	v_fmac_f32_e32 v245, v45, v88
	v_fmac_f32_e32 v246, v43, v49
	v_fmac_f32_e32 v247, v43, v50
	v_fmac_f32_e32 v248, v43, v51
	v_fmac_f32_e32 v249, v43, v52
	v_fmac_f32_e32 v250, v43, v54
	v_fmac_f32_e32 v251, v43, v55
	v_fmac_f32_e32 v252, v43, v56
	v_fmac_f32_e32 v253, v43, v58
	v_mul_f32_e32 v60, 0xbfb8aa3b, v89
	v_mul_f32_e32 v63, 0xbfb8aa3b, v90
	v_mul_f32_e32 v68, 0xbfb8aa3b, v91
	v_mul_f32_e32 v69, 0xbfb8aa3b, v92
	v_mul_f32_e32 v70, 0xbfb8aa3b, v93
	v_mul_f32_e32 v72, 0xbfb8aa3b, v94
	v_mul_f32_e32 v74, 0xbfb8aa3b, v95
	v_mul_f32_e32 v76, 0xbfb8aa3b, v245
	v_exp_f32_e32 v60, v60
	v_exp_f32_e32 v63, v63
	v_exp_f32_e32 v68, v68
	v_exp_f32_e32 v69, v69
	v_exp_f32_e32 v70, v70
	v_exp_f32_e32 v72, v72
	v_exp_f32_e32 v74, v74
	v_exp_f32_e32 v76, v76
	v_add_f32_e32 v60, 1.0, v60
	v_add_f32_e32 v63, 1.0, v63
	v_add_f32_e32 v68, 1.0, v68
	v_add_f32_e32 v69, 1.0, v69
	v_add_f32_e32 v70, 1.0, v70
	v_add_f32_e32 v72, 1.0, v72
	v_add_f32_e32 v74, 1.0, v74
	v_add_f32_e32 v76, 1.0, v76
	v_rcp_f32_e32 v60, v60
	v_rcp_f32_e32 v63, v63
	v_rcp_f32_e32 v68, v68
	v_rcp_f32_e32 v69, v69
	v_rcp_f32_e32 v70, v70
	v_rcp_f32_e32 v72, v72
	v_rcp_f32_e32 v74, v74
	v_rcp_f32_e32 v76, v76
	v_mul_f32_e32 v89, v89, v60
	v_mul_f32_e32 v90, v90, v63
	v_mul_f32_e32 v91, v91, v68
	v_mul_f32_e32 v92, v92, v69
	v_mul_f32_e32 v93, v93, v70
	v_mul_f32_e32 v94, v94, v72
	v_mul_f32_e32 v95, v95, v74
	v_mul_f32_e32 v245, v245, v76
	v_mul_f32_e32 v60, 0xbfb8aa3b, v246
	v_mul_f32_e32 v63, 0xbfb8aa3b, v247
	v_mul_f32_e32 v68, 0xbfb8aa3b, v248
	v_mul_f32_e32 v69, 0xbfb8aa3b, v249
	v_mul_f32_e32 v70, 0xbfb8aa3b, v250
	v_mul_f32_e32 v72, 0xbfb8aa3b, v251
	v_mul_f32_e32 v74, 0xbfb8aa3b, v252
	v_mul_f32_e32 v76, 0xbfb8aa3b, v253
	v_exp_f32_e32 v60, v60
	v_exp_f32_e32 v63, v63
	v_exp_f32_e32 v68, v68
	v_exp_f32_e32 v69, v69
	v_exp_f32_e32 v70, v70
	v_exp_f32_e32 v72, v72
	v_exp_f32_e32 v74, v74
	v_exp_f32_e32 v76, v76
	v_add_f32_e32 v60, 1.0, v60
	v_add_f32_e32 v63, 1.0, v63
	v_add_f32_e32 v68, 1.0, v68
	v_add_f32_e32 v69, 1.0, v69
	v_add_f32_e32 v70, 1.0, v70
	v_add_f32_e32 v72, 1.0, v72
	v_add_f32_e32 v74, 1.0, v74
	v_add_f32_e32 v76, 1.0, v76
	v_rcp_f32_e32 v60, v60
	v_rcp_f32_e32 v63, v63
	v_rcp_f32_e32 v68, v68
	v_rcp_f32_e32 v69, v69
	v_rcp_f32_e32 v70, v70
	v_rcp_f32_e32 v72, v72
	v_rcp_f32_e32 v74, v74
	v_rcp_f32_e32 v76, v76
	v_mul_f32_e32 v246, v246, v60
	v_mul_f32_e32 v247, v247, v63
	v_mul_f32_e32 v248, v248, v68
	v_mul_f32_e32 v249, v249, v69
	v_mul_f32_e32 v250, v250, v70
	v_mul_f32_e32 v251, v251, v72
	v_mul_f32_e32 v252, v252, v74
	v_mul_f32_e32 v253, v253, v76
	v_cvt_pk_bf16_f32 v89, v89, v246
	v_cvt_pk_bf16_f32 v90, v90, v247
	v_cvt_pk_bf16_f32 v91, v91, v248
	v_cvt_pk_bf16_f32 v92, v92, v249
	v_cvt_pk_bf16_f32 v93, v93, v250
	v_cvt_pk_bf16_f32 v94, v94, v251
	v_cvt_pk_bf16_f32 v95, v95, v252
	v_cvt_pk_bf16_f32 v245, v245, v253
	ds_write_b32 v38, v89 offset:18432
	ds_write_b32 v38, v90 offset:18576
	ds_write_b32 v38, v91 offset:18720
	ds_write_b32 v38, v92 offset:18864
	ds_write_b32 v38, v93 offset:19008
	ds_write_b32 v38, v94 offset:19152
	ds_write_b32 v38, v95 offset:19296
	ds_write_b32 v38, v245 offset:19440
	s_mov_b32 s95, 64
	v_and_b32_e32 v167, 63, v96
	v_cmp_gt_i32_e64 s[8:9], 64, v96
	s_branch .Lcv_join
.Lcv_join:
	s_and_saveexec_b64 s[0:1], s[8:9]
	s_cbranch_execz .LBB0_675
	v_cmp_gt_i32_e32 vcc, s95, v96
	v_mov_b32_e32 v36, 0
	v_mov_b32_e32 v37, 0
	s_and_saveexec_b64 s[4:5], vcc
	s_cbranch_execz .LBB0_674
	v_add_f32_e32 v37, v98, v100
	s_mov_b32 s6, 0xbfb8aa3b
	v_mul_f32_e64 v38, |v37|, s6
	v_exp_f32_e32 v52, v38
	v_mul_f32_e32 v36, 0xbfb8aa3b, v99
	v_exp_f32_e32 v36, v36
	v_max_f32_e32 v37, 0, v37
	v_add_f32_e32 v40, 1.0, v52
	v_add_f32_e32 v38, -1.0, v40
	v_sub_f32_e32 v39, v38, v40
	v_add_f32_e32 v39, 1.0, v39
	v_sub_f32_e32 v38, v52, v38
	v_add_f32_e32 v41, v38, v39
	v_frexp_mant_f32_e32 v42, v40
	v_cvt_f64_f32_e32 v[38:39], v40
	v_frexp_exp_i32_f64_e32 v38, v[38:39]
	v_cmp_gt_f32_e32 vcc, s83, v42
	v_add_f32_e32 v36, 1.0, v36
	v_rcp_f32_e32 v36, v36
	v_subbrev_co_u32_e32 v46, vcc, 0, v38, vcc
	v_sub_u32_e32 v38, 0, v46
	v_ldexp_f32 v39, v40, v38
	v_add_f32_e32 v40, -1.0, v39
	v_add_f32_e32 v42, 1.0, v39
	v_ldexp_f32 v38, v41, v38
	v_add_f32_e32 v41, 1.0, v40
	v_add_f32_e32 v43, -1.0, v42
	v_sub_f32_e32 v41, v39, v41
	v_sub_f32_e32 v39, v39, v43
	v_add_f32_e32 v41, v38, v41
	v_add_f32_e32 v38, v38, v39
	v_add_f32_e32 v47, v42, v38
	v_rcp_f32_e32 v49, v47
	v_sub_f32_e32 v39, v47, v42
	v_sub_f32_e32 v48, v38, v39
	v_add_f32_e32 v39, v40, v41
	v_mul_f32_e32 v51, v39, v49
	v_sub_f32_e32 v38, v39, v40
	v_mul_f32_e32 v40, v47, v51
	v_fma_f32 v42, v51, v47, -v40
	v_fmac_f32_e32 v42, v51, v48
	v_sub_f32_e32 v50, v41, v38
	v_add_f32_e32 v38, v40, v42
	v_sub_f32_e32 v41, v39, v38
	v_pk_add_f32 v[44:45], v[38:39], v[40:41] neg_lo:[0,1] neg_hi:[0,1]
	v_mov_b32_e32 v43, v38
	v_pk_add_f32 v[38:39], v[44:45], v[42:43] neg_lo:[0,1] neg_hi:[0,1]
	v_cmp_neq_f32_e32 vcc, s85, v52
	v_add_f32_e32 v39, v50, v39
	v_add_f32_e32 v38, v38, v39
	v_add_f32_e32 v39, v41, v38
	v_mul_f32_e32 v50, v49, v39
	v_mul_f32_e32 v40, v47, v50
	v_fma_f32 v42, v50, v47, -v40
	v_fmac_f32_e32 v42, v50, v48
	v_sub_f32_e32 v41, v41, v39
	v_add_f32_e32 v47, v38, v41
	v_add_f32_e32 v38, v40, v42
	v_sub_f32_e32 v41, v39, v38
	v_pk_add_f32 v[44:45], v[38:39], v[40:41] neg_lo:[0,1] neg_hi:[0,1]
	v_mov_b32_e32 v43, v38
	v_pk_add_f32 v[38:39], v[44:45], v[42:43] neg_lo:[0,1] neg_hi:[0,1]
	s_nop 0
	v_add_f32_e32 v39, v47, v39
	v_add_f32_e32 v38, v38, v39
	v_add_f32_e32 v39, v51, v50
	v_add_f32_e32 v38, v41, v38
	v_sub_f32_e32 v40, v39, v51
	v_mul_f32_e32 v38, v49, v38
	v_sub_f32_e32 v40, v50, v40
	v_add_f32_e32 v40, v40, v38
	v_add_f32_e32 v42, v39, v40
	v_mul_f32_e32 v43, v42, v42
	v_fmamk_f32 v38, v43, 0x3e9b6dac, v154
	v_fmaak_f32 v109, v43, v38, 0x3f2aaada
	v_cvt_f32_i32_e32 v38, v46
	v_sub_f32_e32 v39, v42, v39
	v_sub_f32_e32 v39, v40, v39
	v_ldexp_f32 v44, v39, 1
	v_mul_f32_e32 v39, v42, v43
	v_ldexp_f32 v41, v42, 1
	v_pk_mul_f32 v[42:43], v[38:39], v[108:109]
	s_nop 0
	v_fma_f32 v40, v38, s84, -v42
	v_fmac_f32_e32 v40, 0xb102e308, v38
	v_pk_add_f32 v[38:39], v[42:43], v[40:41]
	s_nop 0
	v_sub_f32_e32 v41, v39, v41
	v_sub_f32_e32 v41, v43, v41
	v_add_f32_e32 v45, v44, v41
	v_mov_b32_e32 v44, v42
	v_pk_add_f32 v[42:43], v[38:39], v[42:43] neg_lo:[0,1] neg_hi:[0,1]
	v_pk_add_f32 v[46:47], v[38:39], v[44:45]
	v_mov_b32_e32 v41, v38
	v_mov_b32_e32 v43, v47
	v_pk_add_f32 v[48:49], v[40:41], v[42:43] neg_lo:[0,1] neg_hi:[0,1]
	v_pk_add_f32 v[40:41], v[40:41], v[42:43]
	v_mov_b32_e32 v44, v45
	v_pk_add_f32 v[42:43], v[40:41], v[38:39] op_sel:[1,0] op_sel_hi:[0,1] neg_lo:[0,1] neg_hi:[0,1]
	v_pk_add_f32 v[50:51], v[46:47], v[42:43] op_sel_hi:[1,0] neg_lo:[0,1] neg_hi:[0,1]
	v_mov_b32_e32 v46, v47
	v_mov_b32_e32 v47, v41
	v_pk_mov_b32 v[42:43], v[38:39], v[42:43] op_sel:[1,0]
	v_mov_b32_e32 v45, v38
	v_pk_add_f32 v[42:43], v[46:47], v[42:43] neg_lo:[0,1] neg_hi:[0,1]
	v_mov_b32_e32 v50, v48
	v_pk_add_f32 v[38:39], v[44:45], v[42:43] neg_lo:[0,1] neg_hi:[0,1]
	v_mov_b32_e32 v49, v41
	v_pk_add_f32 v[42:43], v[50:51], v[38:39]
	s_nop 0
	v_pk_add_f32 v[44:45], v[42:43], v[42:43] op_sel:[0,1] op_sel_hi:[1,0]
	s_nop 0
	v_pk_add_f32 v[40:41], v[40:41], v[44:45] op_sel:[1,0] op_sel_hi:[0,1]
	v_mov_b32_e32 v43, v40
	v_pk_add_f32 v[46:47], v[42:43], v[48:49] neg_lo:[0,1] neg_hi:[0,1]
	v_mov_b32_e32 v39, v44
	v_sub_f32_e32 v41, v42, v46
	v_pk_add_f32 v[38:39], v[38:39], v[46:47] neg_lo:[0,1] neg_hi:[0,1]
	v_sub_f32_e32 v41, v48, v41
	v_add_f32_e32 v38, v38, v41
	v_add_f32_e32 v38, v38, v39
	v_add_f32_e32 v38, v40, v38
	v_cndmask_b32_e32 v38, v155, v38, vcc
	v_cmp_ngt_f32_e32 vcc, -1.0, v52
	v_mul_f32_e32 v39, 0x3fb8aa3b, v97
	v_exp_f32_e32 v39, v39
	v_cndmask_b32_e32 v38, v156, v38, vcc
	v_cmp_neq_f32_e32 vcc, -1.0, v52
	s_nop 1
	v_cndmask_b32_e32 v38, v157, v38, vcc
	v_cmp_lt_f32_e64 vcc, |v52|, s86
	s_nop 1
	v_cndmask_b32_e32 v38, v38, v52, vcc
	v_add_f32_e32 v37, v37, v38
	v_mul_f32_e64 v37, v37, -v39

	.amdhsa_kernel _Z14fwd_megakernel6Params
		.amdhsa_group_segment_fixed_size 73728
		.amdhsa_private_segment_fixed_size 0
		.amdhsa_kernarg_size 392
		.amdhsa_user_sgpr_count 2
		.amdhsa_user_sgpr_dispatch_ptr 0
		.amdhsa_user_sgpr_queue_ptr 0
		.amdhsa_user_sgpr_kernarg_segment_ptr 1
		.amdhsa_user_sgpr_dispatch_id 0
		.amdhsa_user_sgpr_kernarg_preload_length 0
		.amdhsa_user_sgpr_kernarg_preload_offset 0
		.amdhsa_user_sgpr_private_segment_size 0
		.amdhsa_uses_dynamic_stack 0
		.amdhsa_enable_private_segment 0
		.amdhsa_system_sgpr_workgroup_id_x 1
		.amdhsa_system_sgpr_workgroup_id_y 0
		.amdhsa_system_sgpr_workgroup_id_z 0
		.amdhsa_system_sgpr_workgroup_info 0
		.amdhsa_system_vgpr_workitem_id 2
		.amdhsa_next_free_vgpr 256
		.amdhsa_next_free_sgpr 102
		.amdhsa_accum_offset 256
		.amdhsa_reserve_vcc 1
		.amdhsa_float_round_mode_32 0
		.amdhsa_float_round_mode_16_64 0
		.amdhsa_float_denorm_mode_32 3
		.amdhsa_float_denorm_mode_16_64 3
		.amdhsa_dx10_clamp 1
		.amdhsa_ieee_mode 1
		.amdhsa_fp16_overflow 0
		.amdhsa_tg_split 0
		.amdhsa_exception_fp_ieee_invalid_op 0
		.amdhsa_exception_fp_denorm_src 0
		.amdhsa_exception_fp_ieee_div_zero 0
		.amdhsa_exception_fp_ieee_overflow 0
		.amdhsa_exception_fp_ieee_underflow 0
		.amdhsa_exception_fp_ieee_inexact 0
		.amdhsa_exception_int_div_zero 0
	.end_amdhsa_kernel

amdhsa.kernels:
  - .agpr_count:     0
    .args:
      - .offset:         0
        .size:           136
        .value_kind:     by_value
      - .offset:         136
        .size:           4
        .value_kind:     hidden_block_count_x
      - .offset:         140
        .size:           4
        .value_kind:     hidden_block_count_y
      - .offset:         144
        .size:           4
        .value_kind:     hidden_block_count_z
      - .offset:         148
        .size:           2
        .value_kind:     hidden_group_size_x
      - .offset:         150
        .size:           2
        .value_kind:     hidden_group_size_y
      - .offset:         152
        .size:           2
        .value_kind:     hidden_group_size_z
      - .offset:         154
        .size:           2
        .value_kind:     hidden_remainder_x
      - .offset:         156
        .size:           2
        .value_kind:     hidden_remainder_y
      - .offset:         158
        .size:           2
        .value_kind:     hidden_remainder_z
      - .offset:         176
        .size:           8
        .value_kind:     hidden_global_offset_x
      - .offset:         184
        .size:           8
        .value_kind:     hidden_global_offset_y
      - .offset:         192
        .size:           8
        .value_kind:     hidden_global_offset_z
      - .offset:         200
        .size:           2
        .value_kind:     hidden_grid_dims
      - .offset:         224
        .size:           8
        .value_kind:     hidden_multigrid_sync_arg
    .group_segment_fixed_size: 73728
    .kernarg_segment_align: 8
    .kernarg_segment_size: 392
    .language:       OpenCL C
    .language_version:
      - 2
      - 0
    .max_flat_workgroup_size: 256
    .name:           _Z14fwd_megakernel6Params
    .private_segment_fixed_size: 0
    .sgpr_count:     108
    .sgpr_spill_count: 6
    .symbol:         _Z14fwd_megakernel6Params.kd
    .uniform_work_group_size: 1
    .uses_dynamic_stack: false
    .vgpr_count:     256
    .vgpr_spill_count: 0
    .wavefront_size: 64
